# attention tile loop: K/V fragment loads via SGPR base + precomputed lane offsets (no per-load VALU address math), bias tile read directly into accumulators, swap-moves folded into cvt; branchless LoRA
# speedup vs baseline: 1.0366x; 1.0026x over previous
; #define LAS __attribute__((address_space(3)))
; __device__ __forceinline__ unsigned pk2(float lo, float hi) { const f32x2c v = {lo, hi}; const bf16x2c b = __builtin_convertvector(v, bf16x2c); return __builtin_bit_cast(unsigned, b); }
; __device__ __forceinline__ float bflo(unsigned w) { return __uint_as_float(w << 16); }
; __device__ __forceinline__ float bfhi(unsigned w) { return __uint_as_float(w & 0xffff0000u); }
; __device__ __forceinline__ float fast_sigmoid(float x) { return __builtin_amdgcn_rcpf(1.f + __expf(-x)); }
; #define lane (lane_now())
; __device__ __forceinline__ f32x4 lerp4(const bf16_t* cur, const bf16_t* prv, bool first, const float* mu) {
;     const u32x2 a = *(const u32x2*)cur; u32x2 q = *(const u32x2*)prv; if (first) { q.x = 0u; q.y = 0u; }
;     const f32x4 m = *(const f32x4*)mu;
;     const f32x4 x = {bflo(a.x), bfhi(a.x), bflo(a.y), bfhi(a.y)}, y = {bflo(q.x), bfhi(q.x), bflo(q.y), bfhi(q.y)};
;     return x + (y - x) * m;
; }
; __device__ __forceinline__ void prep_rwkv_phase(const Params& p, LAS unsigned char* lds, int gw, int ngw, int wave, int lane) {
;     ...
;     const int item = gw + kit * ngw; const bool active = item < ntiles;
;     const int m0 = (active ? item : 0) * 16, b = m0 >> 13;
;     u32x4 wreg[4]; prep_w_load(p, 0, tid, wreg);
;     if (active) {
;         const int tk = lane >> 2, cq = lane & 3, m = m0 + tk; const bool first = (m & 8191) == 0;
;         const bf16_t* pr = PA + (size_t)m * NPA + 1536 + cq * 64; const bf16_t* pp = first ? pr : pr - NPA;
; #pragma unroll
;         for (int g8 = 0; g8 < 8; ++g8) {
;             const f32x4 x0 = lerp4(pr + g8 * 8, pp + g8 * 8, first, p.mu + 1536 + cq * 64 + g8 * 8);
;             const f32x4 x1 = lerp4(pr + g8 * 8 + 4, pp + g8 * 8 + 4, first, p.mu + 1536 + cq * 64 + g8 * 8 + 4);
;             float v[8] = {x0.x, x0.y, x0.z, x0.w, x1.x, x1.y, x1.z, x1.w};
; #pragma unroll
;             for (int e = 0; e < 8; ++e) { if (cq == 0) v[e] = 1.f - 2.f * __builtin_amdgcn_rcpf(__expf(2.f * v[e]) + 1.f); else if (cq >= 2) v[e] = fast_sigmoid(v[e]); }
;             u32x4 w; w.x = pk2(v[0], v[1]); w.y = pk2(v[2], v[3]); w.z = pk2(v[4], v[5]); w.w = pk2(v[6], v[7]);
;             *(LAS u32x4*)(act + tk * 264 + cq * 64 + g8 * 8) = w;
;         }
.LBB0_467:
	global_load_dwordx4 v[4:7], v[100:101], off
	global_load_dwordx4 v[8:11], v[102:103], off
	global_load_dwordx4 v[12:15], v[104:105], off
	global_load_dwordx4 v[16:19], v[106:107], off
	s_mul_i32 s6, s24, s84
	s_add_i32 s6, s6, s78
	s_cmpk_lt_i32 s6, 0x800
	s_cselect_b64 s[20:21], -1, 0
	s_lshl_b32 s30, s6, 4
	s_cmpk_gt_i32 s6, 0x7ff
	s_cbranch_scc1 .LBB0_853
	s_waitcnt lgkmcnt(0)
	v_mov_b32_e32 v245, 0xbfb8aa3b
	v_mov_b32_e32 v246, 1.0
	v_mov_b32_e32 v247, 0
	v_mov_b32_e32 v2, 0x4038aa3b
	v_cmp_eq_u32_e32 vcc, 0, v207
	v_cmp_eq_u32_e64 s[98:99], 1, v207
	s_nop 1
	v_cndmask_b32_e32 v245, v245, v2, vcc
	v_cndmask_b32_e64 v246, v246, -2.0, vcc
	v_cndmask_b32_e64 v247, v247, 1.0, vcc
	v_add_u32_e32 v2, s30, v206
	v_mad_i64_i32 v[0:1], s[6:7], v2, s26, v[124:125]
	v_and_b32_e32 v2, 0x1fff, v2
	v_cmp_eq_u32_e32 vcc, 0, v2
	global_load_dwordx4 v[22:25], v[0:1], off offset:3072
	v_cmp_lt_i32_e64 s[6:7], 0, v207
	v_cndmask_b32_e64 v21, -1, 0, vcc
	v_cndmask_b32_e64 v20, v224, 0, vcc
	v_lshl_add_u64 v[20:21], v[0:1], 0, v[20:21]
	global_load_dwordx4 v[26:29], v[20:21], off offset:3072
	global_load_dwordx4 v[30:33], v[108:109], off
	global_load_dwordx4 v[34:37], v[108:109], off offset:16
	s_waitcnt vmcnt(3)
	v_lshlrev_b32_e32 v40, 16, v24
	v_and_b32_e32 v41, 0xffff0000, v24
	v_lshlrev_b32_e32 v42, 16, v25
	v_and_b32_e32 v43, 0xffff0000, v25
	s_waitcnt vmcnt(2)
	v_cndmask_b32_e64 v2, v27, 0, vcc
	v_cndmask_b32_e64 v24, v26, 0, vcc
	v_cndmask_b32_e64 v25, v29, 0, vcc
	v_cndmask_b32_e64 v26, v28, 0, vcc
	v_lshlrev_b32_e32 v38, 16, v22
	v_and_b32_e32 v39, 0xffff0000, v22
	v_lshlrev_b32_e32 v22, 16, v23
	v_and_b32_e32 v23, 0xffff0000, v23
	v_lshlrev_b32_e32 v27, 16, v24
	v_and_b32_e32 v24, 0xffff0000, v24
	v_lshlrev_b32_e32 v28, 16, v2
	v_and_b32_e32 v2, 0xffff0000, v2
	v_lshlrev_b32_e32 v44, 16, v26
	v_and_b32_e32 v29, 0xffff0000, v26
	v_lshlrev_b32_e32 v46, 16, v25
	v_and_b32_e32 v45, 0xffff0000, v25
	v_sub_f32_e32 v25, v24, v39
	v_sub_f32_e32 v24, v27, v38
	v_sub_f32_e32 v27, v2, v23
	v_sub_f32_e32 v26, v28, v22
	v_sub_f32_e32 v29, v29, v41
	v_sub_f32_e32 v28, v44, v40
	v_sub_f32_e32 v45, v45, v43
	v_sub_f32_e32 v44, v46, v42
	s_waitcnt vmcnt(1)
	v_pk_fma_f32 v[22:23], v[32:33], v[26:27], v[22:23]
	v_pk_fma_f32 v[24:25], v[30:31], v[24:25], v[38:39]
	s_waitcnt vmcnt(0)
	v_pk_fma_f32 v[26:27], v[36:37], v[44:45], v[42:43]
	v_pk_fma_f32 v[28:29], v[34:35], v[28:29], v[40:41]
	v_mul_f32_e32 v240, v245, v24
	v_mul_f32_e32 v241, v245, v25
	v_mul_f32_e32 v242, v245, v22
	v_mul_f32_e32 v243, v245, v23
	v_exp_f32_e32 v240, v240
	v_exp_f32_e32 v241, v241
	v_exp_f32_e32 v242, v242
	v_exp_f32_e32 v243, v243
	v_add_f32_e32 v240, 1.0, v240
	v_add_f32_e32 v241, 1.0, v241
	v_add_f32_e32 v242, 1.0, v242
	v_add_f32_e32 v243, 1.0, v243
	v_rcp_f32_e32 v240, v240
	v_rcp_f32_e32 v241, v241
	v_rcp_f32_e32 v242, v242
	v_rcp_f32_e32 v243, v243
	v_fma_f32 v240, v240, v246, v247
	v_fma_f32 v241, v241, v246, v247
	v_fma_f32 v242, v242, v246, v247
	v_fma_f32 v243, v243, v246, v247
	v_cndmask_b32_e64 v24, v240, v24, s[98:99]
	v_cndmask_b32_e64 v25, v241, v25, s[98:99]
	v_cndmask_b32_e64 v22, v242, v22, s[98:99]
	v_cndmask_b32_e64 v23, v243, v23, s[98:99]
	v_mul_f32_e32 v240, v245, v28
	v_mul_f32_e32 v241, v245, v29
	v_mul_f32_e32 v242, v245, v26
	v_mul_f32_e32 v243, v245, v27
	v_exp_f32_e32 v240, v240
	v_exp_f32_e32 v241, v241
	v_exp_f32_e32 v242, v242
	v_exp_f32_e32 v243, v243
	v_add_f32_e32 v240, 1.0, v240
	v_add_f32_e32 v241, 1.0, v241
	v_add_f32_e32 v242, 1.0, v242
	v_add_f32_e32 v243, 1.0, v243
	v_rcp_f32_e32 v240, v240
	v_rcp_f32_e32 v241, v241
	v_rcp_f32_e32 v242, v242
	v_rcp_f32_e32 v243, v243
	v_fma_f32 v240, v240, v246, v247
	v_fma_f32 v241, v241, v246, v247
	v_fma_f32 v242, v242, v246, v247
	v_fma_f32 v243, v243, v246, v247
	v_cndmask_b32_e64 v28, v240, v28, s[98:99]
	v_cndmask_b32_e64 v29, v241, v29, s[98:99]
	v_cndmask_b32_e64 v26, v242, v26, s[98:99]
	v_cndmask_b32_e64 v27, v243, v27, s[98:99]
	v_cvt_pk_bf16_f32 v30, v24, v25
	v_cvt_pk_bf16_f32 v31, v22, v23
	v_cvt_pk_bf16_f32 v32, v28, v29
	v_cvt_pk_bf16_f32 v33, v26, v27
	ds_write_b128 v208, v[30:33]
	global_load_dwordx4 v[22:25], v[20:21], off offset:3088
	global_load_dwordx4 v[26:29], v[0:1], off offset:3088
	global_load_dwordx4 v[30:33], v[110:111], off
	global_load_dwordx4 v[34:37], v[110:111], off offset:16
	v_cmp_lt_i32_e64 s[6:7], 0, v207
	s_waitcnt vmcnt(3)
	v_cndmask_b32_e64 v2, v23, 0, vcc
	v_cndmask_b32_e64 v42, v22, 0, vcc
	v_cndmask_b32_e64 v25, v25, 0, vcc
	v_cndmask_b32_e64 v24, v24, 0, vcc
	s_waitcnt vmcnt(2)
	v_lshlrev_b32_e32 v38, 16, v26
	v_and_b32_e32 v39, 0xffff0000, v26
	v_lshlrev_b32_e32 v22, 16, v27
	v_and_b32_e32 v23, 0xffff0000, v27
	v_lshlrev_b32_e32 v40, 16, v28
	v_and_b32_e32 v41, 0xffff0000, v28
	v_lshlrev_b32_e32 v26, 16, v29
	v_and_b32_e32 v27, 0xffff0000, v29
	v_lshlrev_b32_e32 v28, 16, v42
	v_and_b32_e32 v29, 0xffff0000, v42
	v_lshlrev_b32_e32 v42, 16, v2
	v_and_b32_e32 v2, 0xffff0000, v2
	v_lshlrev_b32_e32 v44, 16, v24
	v_and_b32_e32 v43, 0xffff0000, v24
	v_lshlrev_b32_e32 v46, 16, v25
	v_and_b32_e32 v45, 0xffff0000, v25
	v_sub_f32_e32 v25, v29, v39
	v_sub_f32_e32 v24, v28, v38
	v_sub_f32_e32 v29, v2, v23
	v_sub_f32_e32 v28, v42, v22
	v_sub_f32_e32 v43, v43, v41
	v_sub_f32_e32 v42, v44, v40
	v_sub_f32_e32 v45, v45, v27
	v_sub_f32_e32 v44, v46, v26
	s_waitcnt vmcnt(1)
	v_pk_fma_f32 v[22:23], v[32:33], v[28:29], v[22:23]
	v_pk_fma_f32 v[24:25], v[30:31], v[24:25], v[38:39]
	s_waitcnt vmcnt(0)
; #define LAS __attribute__((address_space(3)))
; __device__ __forceinline__ unsigned pk2(float lo, float hi) { const f32x2c v = {lo, hi}; const bf16x2c b = __builtin_convertvector(v, bf16x2c); return __builtin_bit_cast(unsigned, b); }
; __device__ __forceinline__ float bflo(unsigned w) { return __uint_as_float(w << 16); }
; __device__ __forceinline__ float bfhi(unsigned w) { return __uint_as_float(w & 0xffff0000u); }
; __device__ __forceinline__ float fast_sigmoid(float x) { return __builtin_amdgcn_rcpf(1.f + __expf(-x)); }
; __device__ __forceinline__ f32x4 lerp4(const bf16_t* cur, const bf16_t* prv, bool first, const float* mu) {
;     const u32x2 a = *(const u32x2*)cur; u32x2 q = *(const u32x2*)prv; if (first) { q.x = 0u; q.y = 0u; }
;     const f32x4 m = *(const f32x4*)mu;
;     const f32x4 x = {bflo(a.x), bfhi(a.x), bflo(a.y), bfhi(a.y)}, y = {bflo(q.x), bfhi(q.x), bflo(q.y), bfhi(q.y)};
;     return x + (y - x) * m;
; }
; __device__ __forceinline__ void prep_rwkv_phase(const Params& p, LAS unsigned char* lds, int gw, int ngw, int wave, int lane) {
;     ...
;         for (int g8 = 0; g8 < 8; ++g8) {
;             const f32x4 x0 = lerp4(pr + g8 * 8, pp + g8 * 8, first, p.mu + 1536 + cq * 64 + g8 * 8);
;             const f32x4 x1 = lerp4(pr + g8 * 8 + 4, pp + g8 * 8 + 4, first, p.mu + 1536 + cq * 64 + g8 * 8 + 4);
;             float v[8] = {x0.x, x0.y, x0.z, x0.w, x1.x, x1.y, x1.z, x1.w};
; #pragma unroll
;             for (int e = 0; e < 8; ++e) { if (cq == 0) v[e] = 1.f - 2.f * __builtin_amdgcn_rcpf(__expf(2.f * v[e]) + 1.f); else if (cq >= 2) v[e] = fast_sigmoid(v[e]); }
;             u32x4 w; w.x = pk2(v[0], v[1]); w.y = pk2(v[2], v[3]); w.z = pk2(v[4], v[5]); w.w = pk2(v[6], v[7]);
;             *(LAS u32x4*)(act + tk * 264 + cq * 64 + g8 * 8) = w;
;         }
	v_pk_fma_f32 v[26:27], v[36:37], v[44:45], v[26:27]
	v_pk_fma_f32 v[28:29], v[34:35], v[42:43], v[40:41]
	v_mul_f32_e32 v240, v245, v24
	v_mul_f32_e32 v241, v245, v25
	v_mul_f32_e32 v242, v245, v22
	v_mul_f32_e32 v243, v245, v23
	v_exp_f32_e32 v240, v240
	v_exp_f32_e32 v241, v241
	v_exp_f32_e32 v242, v242
	v_exp_f32_e32 v243, v243
	v_add_f32_e32 v240, 1.0, v240
	v_add_f32_e32 v241, 1.0, v241
	v_add_f32_e32 v242, 1.0, v242
	v_add_f32_e32 v243, 1.0, v243
	v_rcp_f32_e32 v240, v240
	v_rcp_f32_e32 v241, v241
	v_rcp_f32_e32 v242, v242
	v_rcp_f32_e32 v243, v243
	v_fma_f32 v240, v240, v246, v247
	v_fma_f32 v241, v241, v246, v247
	v_fma_f32 v242, v242, v246, v247
	v_fma_f32 v243, v243, v246, v247
	v_cndmask_b32_e64 v24, v240, v24, s[98:99]
	v_cndmask_b32_e64 v25, v241, v25, s[98:99]
	v_cndmask_b32_e64 v22, v242, v22, s[98:99]
	v_cndmask_b32_e64 v23, v243, v23, s[98:99]
	v_mul_f32_e32 v240, v245, v28
	v_mul_f32_e32 v241, v245, v29
	v_mul_f32_e32 v242, v245, v26
	v_mul_f32_e32 v243, v245, v27
	v_exp_f32_e32 v240, v240
	v_exp_f32_e32 v241, v241
	v_exp_f32_e32 v242, v242
	v_exp_f32_e32 v243, v243
	v_add_f32_e32 v240, 1.0, v240
	v_add_f32_e32 v241, 1.0, v241
	v_add_f32_e32 v242, 1.0, v242
	v_add_f32_e32 v243, 1.0, v243
	v_rcp_f32_e32 v240, v240
	v_rcp_f32_e32 v241, v241
	v_rcp_f32_e32 v242, v242
	v_rcp_f32_e32 v243, v243
	v_fma_f32 v240, v240, v246, v247
	v_fma_f32 v241, v241, v246, v247
	v_fma_f32 v242, v242, v246, v247
	v_fma_f32 v243, v243, v246, v247
	v_cndmask_b32_e64 v28, v240, v28, s[98:99]
	v_cndmask_b32_e64 v29, v241, v29, s[98:99]
	v_cndmask_b32_e64 v26, v242, v26, s[98:99]
	v_cndmask_b32_e64 v27, v243, v27, s[98:99]
	v_cvt_pk_bf16_f32 v30, v24, v25
	v_cvt_pk_bf16_f32 v31, v22, v23
	v_cvt_pk_bf16_f32 v32, v28, v29
	v_cvt_pk_bf16_f32 v33, v26, v27
	ds_write_b128 v208, v[30:33] offset:16
	global_load_dwordx4 v[22:25], v[20:21], off offset:3104
	global_load_dwordx4 v[26:29], v[0:1], off offset:3104
	global_load_dwordx4 v[30:33], v[112:113], off
	global_load_dwordx4 v[34:37], v[112:113], off offset:16
	v_cmp_lt_i32_e64 s[6:7], 0, v207
	s_waitcnt vmcnt(3)
	v_cndmask_b32_e64 v2, v23, 0, vcc
	v_cndmask_b32_e64 v42, v22, 0, vcc
	v_cndmask_b32_e64 v25, v25, 0, vcc
	v_cndmask_b32_e64 v24, v24, 0, vcc
	s_waitcnt vmcnt(2)
	v_lshlrev_b32_e32 v38, 16, v26
	v_and_b32_e32 v39, 0xffff0000, v26
	v_lshlrev_b32_e32 v22, 16, v27
	v_and_b32_e32 v23, 0xffff0000, v27
	v_lshlrev_b32_e32 v40, 16, v28
	v_and_b32_e32 v41, 0xffff0000, v28
	v_lshlrev_b32_e32 v26, 16, v29
	v_and_b32_e32 v27, 0xffff0000, v29
	v_lshlrev_b32_e32 v28, 16, v42
	v_and_b32_e32 v29, 0xffff0000, v42
	v_lshlrev_b32_e32 v42, 16, v2
	v_and_b32_e32 v2, 0xffff0000, v2
	v_lshlrev_b32_e32 v44, 16, v24
	v_and_b32_e32 v43, 0xffff0000, v24
	v_lshlrev_b32_e32 v46, 16, v25
	v_and_b32_e32 v45, 0xffff0000, v25
	v_sub_f32_e32 v25, v29, v39
	v_sub_f32_e32 v24, v28, v38
	v_sub_f32_e32 v29, v2, v23
	v_sub_f32_e32 v28, v42, v22
	v_sub_f32_e32 v43, v43, v41
	v_sub_f32_e32 v42, v44, v40
	v_sub_f32_e32 v45, v45, v27
	v_sub_f32_e32 v44, v46, v26
	s_waitcnt vmcnt(1)
	v_pk_fma_f32 v[22:23], v[32:33], v[28:29], v[22:23]
	v_pk_fma_f32 v[24:25], v[30:31], v[24:25], v[38:39]
	s_waitcnt vmcnt(0)
	v_pk_fma_f32 v[26:27], v[36:37], v[44:45], v[26:27]
	v_pk_fma_f32 v[28:29], v[34:35], v[42:43], v[40:41]
	v_mul_f32_e32 v240, v245, v24
	v_mul_f32_e32 v241, v245, v25
	v_mul_f32_e32 v242, v245, v22
	v_mul_f32_e32 v243, v245, v23
	v_exp_f32_e32 v240, v240
	v_exp_f32_e32 v241, v241
	v_exp_f32_e32 v242, v242
	v_exp_f32_e32 v243, v243
	v_add_f32_e32 v240, 1.0, v240
	v_add_f32_e32 v241, 1.0, v241
	v_add_f32_e32 v242, 1.0, v242
	v_add_f32_e32 v243, 1.0, v243
	v_rcp_f32_e32 v240, v240
	v_rcp_f32_e32 v241, v241
	v_rcp_f32_e32 v242, v242
	v_rcp_f32_e32 v243, v243
	v_fma_f32 v240, v240, v246, v247
	v_fma_f32 v241, v241, v246, v247
	v_fma_f32 v242, v242, v246, v247
	v_fma_f32 v243, v243, v246, v247
	v_cndmask_b32_e64 v24, v240, v24, s[98:99]
	v_cndmask_b32_e64 v25, v241, v25, s[98:99]
	v_cndmask_b32_e64 v22, v242, v22, s[98:99]
	v_cndmask_b32_e64 v23, v243, v23, s[98:99]
	v_mul_f32_e32 v240, v245, v28
	v_mul_f32_e32 v241, v245, v29
	v_mul_f32_e32 v242, v245, v26
	v_mul_f32_e32 v243, v245, v27
	v_exp_f32_e32 v240, v240
	v_exp_f32_e32 v241, v241
	v_exp_f32_e32 v242, v242
	v_exp_f32_e32 v243, v243
	v_add_f32_e32 v240, 1.0, v240
	v_add_f32_e32 v241, 1.0, v241
	v_add_f32_e32 v242, 1.0, v242
	v_add_f32_e32 v243, 1.0, v243
	v_rcp_f32_e32 v240, v240
	v_rcp_f32_e32 v241, v241
	v_rcp_f32_e32 v242, v242
	v_rcp_f32_e32 v243, v243
	v_fma_f32 v240, v240, v246, v247
	v_fma_f32 v241, v241, v246, v247
	v_fma_f32 v242, v242, v246, v247
	v_fma_f32 v243, v243, v246, v247
	v_cndmask_b32_e64 v28, v240, v28, s[98:99]
	v_cndmask_b32_e64 v29, v241, v29, s[98:99]
	v_cndmask_b32_e64 v26, v242, v26, s[98:99]
	v_cndmask_b32_e64 v27, v243, v27, s[98:99]
	v_cvt_pk_bf16_f32 v30, v24, v25
	v_cvt_pk_bf16_f32 v31, v22, v23
	v_cvt_pk_bf16_f32 v32, v28, v29
	v_cvt_pk_bf16_f32 v33, v26, v27
	ds_write_b128 v208, v[30:33] offset:32
	global_load_dwordx4 v[22:25], v[20:21], off offset:3120
	global_load_dwordx4 v[26:29], v[0:1], off offset:3120
	global_load_dwordx4 v[30:33], v[114:115], off
	global_load_dwordx4 v[34:37], v[114:115], off offset:16
	v_cmp_lt_i32_e64 s[6:7], 0, v207
	s_waitcnt vmcnt(3)
	v_cndmask_b32_e64 v2, v23, 0, vcc
	v_cndmask_b32_e64 v42, v22, 0, vcc
	v_cndmask_b32_e64 v25, v25, 0, vcc
	v_cndmask_b32_e64 v24, v24, 0, vcc
	s_waitcnt vmcnt(2)
; #define LAS __attribute__((address_space(3)))
; __device__ __forceinline__ unsigned pk2(float lo, float hi) { const f32x2c v = {lo, hi}; const bf16x2c b = __builtin_convertvector(v, bf16x2c); return __builtin_bit_cast(unsigned, b); }
; __device__ __forceinline__ float bflo(unsigned w) { return __uint_as_float(w << 16); }
; __device__ __forceinline__ float bfhi(unsigned w) { return __uint_as_float(w & 0xffff0000u); }
; __device__ __forceinline__ float fast_sigmoid(float x) { return __builtin_amdgcn_rcpf(1.f + __expf(-x)); }
; __device__ __forceinline__ f32x4 lerp4(const bf16_t* cur, const bf16_t* prv, bool first, const float* mu) {
;     const u32x2 a = *(const u32x2*)cur; u32x2 q = *(const u32x2*)prv; if (first) { q.x = 0u; q.y = 0u; }
;     const f32x4 m = *(const f32x4*)mu;
;     const f32x4 x = {bflo(a.x), bfhi(a.x), bflo(a.y), bfhi(a.y)}, y = {bflo(q.x), bfhi(q.x), bflo(q.y), bfhi(q.y)};
;     return x + (y - x) * m;
; }
; __device__ __forceinline__ void prep_rwkv_phase(const Params& p, LAS unsigned char* lds, int gw, int ngw, int wave, int lane) {
;     ...
;         for (int g8 = 0; g8 < 8; ++g8) {
;             const f32x4 x0 = lerp4(pr + g8 * 8, pp + g8 * 8, first, p.mu + 1536 + cq * 64 + g8 * 8);
;             const f32x4 x1 = lerp4(pr + g8 * 8 + 4, pp + g8 * 8 + 4, first, p.mu + 1536 + cq * 64 + g8 * 8 + 4);
;             float v[8] = {x0.x, x0.y, x0.z, x0.w, x1.x, x1.y, x1.z, x1.w};
; #pragma unroll
;             for (int e = 0; e < 8; ++e) { if (cq == 0) v[e] = 1.f - 2.f * __builtin_amdgcn_rcpf(__expf(2.f * v[e]) + 1.f); else if (cq >= 2) v[e] = fast_sigmoid(v[e]); }
;             u32x4 w; w.x = pk2(v[0], v[1]); w.y = pk2(v[2], v[3]); w.z = pk2(v[4], v[5]); w.w = pk2(v[6], v[7]);
;             *(LAS u32x4*)(act + tk * 264 + cq * 64 + g8 * 8) = w;
;         }
	v_lshlrev_b32_e32 v38, 16, v26
	v_and_b32_e32 v39, 0xffff0000, v26
	v_lshlrev_b32_e32 v22, 16, v27
	v_and_b32_e32 v23, 0xffff0000, v27
	v_lshlrev_b32_e32 v40, 16, v28
	v_and_b32_e32 v41, 0xffff0000, v28
	v_lshlrev_b32_e32 v26, 16, v29
	v_and_b32_e32 v27, 0xffff0000, v29
	v_lshlrev_b32_e32 v28, 16, v42
	v_and_b32_e32 v29, 0xffff0000, v42
	v_lshlrev_b32_e32 v42, 16, v2
	v_and_b32_e32 v2, 0xffff0000, v2
	v_lshlrev_b32_e32 v44, 16, v24
	v_and_b32_e32 v43, 0xffff0000, v24
	v_lshlrev_b32_e32 v46, 16, v25
	v_and_b32_e32 v45, 0xffff0000, v25
	v_sub_f32_e32 v25, v29, v39
	v_sub_f32_e32 v24, v28, v38
	v_sub_f32_e32 v29, v2, v23
	v_sub_f32_e32 v28, v42, v22
	v_sub_f32_e32 v43, v43, v41
	v_sub_f32_e32 v42, v44, v40
	v_sub_f32_e32 v45, v45, v27
	v_sub_f32_e32 v44, v46, v26
	s_waitcnt vmcnt(1)
	v_pk_fma_f32 v[22:23], v[32:33], v[28:29], v[22:23]
	v_pk_fma_f32 v[24:25], v[30:31], v[24:25], v[38:39]
	s_waitcnt vmcnt(0)
	v_pk_fma_f32 v[26:27], v[36:37], v[44:45], v[26:27]
	v_pk_fma_f32 v[28:29], v[34:35], v[42:43], v[40:41]
	v_mul_f32_e32 v240, v245, v24
	v_mul_f32_e32 v241, v245, v25
	v_mul_f32_e32 v242, v245, v22
	v_mul_f32_e32 v243, v245, v23
	v_exp_f32_e32 v240, v240
	v_exp_f32_e32 v241, v241
	v_exp_f32_e32 v242, v242
	v_exp_f32_e32 v243, v243
	v_add_f32_e32 v240, 1.0, v240
	v_add_f32_e32 v241, 1.0, v241
	v_add_f32_e32 v242, 1.0, v242
	v_add_f32_e32 v243, 1.0, v243
	v_rcp_f32_e32 v240, v240
	v_rcp_f32_e32 v241, v241
	v_rcp_f32_e32 v242, v242
	v_rcp_f32_e32 v243, v243
	v_fma_f32 v240, v240, v246, v247
	v_fma_f32 v241, v241, v246, v247
	v_fma_f32 v242, v242, v246, v247
	v_fma_f32 v243, v243, v246, v247
	v_cndmask_b32_e64 v24, v240, v24, s[98:99]
	v_cndmask_b32_e64 v25, v241, v25, s[98:99]
	v_cndmask_b32_e64 v22, v242, v22, s[98:99]
	v_cndmask_b32_e64 v23, v243, v23, s[98:99]
	v_mul_f32_e32 v240, v245, v28
	v_mul_f32_e32 v241, v245, v29
	v_mul_f32_e32 v242, v245, v26
	v_mul_f32_e32 v243, v245, v27
	v_exp_f32_e32 v240, v240
	v_exp_f32_e32 v241, v241
	v_exp_f32_e32 v242, v242
	v_exp_f32_e32 v243, v243
	v_add_f32_e32 v240, 1.0, v240
	v_add_f32_e32 v241, 1.0, v241
	v_add_f32_e32 v242, 1.0, v242
	v_add_f32_e32 v243, 1.0, v243
	v_rcp_f32_e32 v240, v240
	v_rcp_f32_e32 v241, v241
	v_rcp_f32_e32 v242, v242
	v_rcp_f32_e32 v243, v243
	v_fma_f32 v240, v240, v246, v247
	v_fma_f32 v241, v241, v246, v247
	v_fma_f32 v242, v242, v246, v247
	v_fma_f32 v243, v243, v246, v247
	v_cndmask_b32_e64 v28, v240, v28, s[98:99]
	v_cndmask_b32_e64 v29, v241, v29, s[98:99]
	v_cndmask_b32_e64 v26, v242, v26, s[98:99]
	v_cndmask_b32_e64 v27, v243, v27, s[98:99]
	v_cvt_pk_bf16_f32 v30, v24, v25
	v_cvt_pk_bf16_f32 v31, v22, v23
	v_cvt_pk_bf16_f32 v32, v28, v29
	v_cvt_pk_bf16_f32 v33, v26, v27
	ds_write_b128 v208, v[30:33] offset:48
	global_load_dwordx4 v[22:25], v[20:21], off offset:3136
	global_load_dwordx4 v[26:29], v[0:1], off offset:3136
	global_load_dwordx4 v[30:33], v[116:117], off
	global_load_dwordx4 v[34:37], v[116:117], off offset:16
	v_cmp_lt_i32_e64 s[6:7], 0, v207
	s_waitcnt vmcnt(3)
	v_cndmask_b32_e64 v2, v23, 0, vcc
	v_cndmask_b32_e64 v42, v22, 0, vcc
	v_cndmask_b32_e64 v25, v25, 0, vcc
	v_cndmask_b32_e64 v24, v24, 0, vcc
	s_waitcnt vmcnt(2)
	v_lshlrev_b32_e32 v38, 16, v26
	v_and_b32_e32 v39, 0xffff0000, v26
	v_lshlrev_b32_e32 v22, 16, v27
	v_and_b32_e32 v23, 0xffff0000, v27
	v_lshlrev_b32_e32 v40, 16, v28
	v_and_b32_e32 v41, 0xffff0000, v28
	v_lshlrev_b32_e32 v26, 16, v29
	v_and_b32_e32 v27, 0xffff0000, v29
	v_lshlrev_b32_e32 v28, 16, v42
	v_and_b32_e32 v29, 0xffff0000, v42
	v_lshlrev_b32_e32 v42, 16, v2
	v_and_b32_e32 v2, 0xffff0000, v2
	v_lshlrev_b32_e32 v44, 16, v24
	v_and_b32_e32 v43, 0xffff0000, v24
	v_lshlrev_b32_e32 v46, 16, v25
	v_and_b32_e32 v45, 0xffff0000, v25
	v_sub_f32_e32 v25, v29, v39
	v_sub_f32_e32 v24, v28, v38
	v_sub_f32_e32 v29, v2, v23
	v_sub_f32_e32 v28, v42, v22
	v_sub_f32_e32 v43, v43, v41
	v_sub_f32_e32 v42, v44, v40
	v_sub_f32_e32 v45, v45, v27
	v_sub_f32_e32 v44, v46, v26
	s_waitcnt vmcnt(1)
	v_pk_fma_f32 v[22:23], v[32:33], v[28:29], v[22:23]
	v_pk_fma_f32 v[24:25], v[30:31], v[24:25], v[38:39]
	s_waitcnt vmcnt(0)
	v_pk_fma_f32 v[26:27], v[36:37], v[44:45], v[26:27]
	v_pk_fma_f32 v[28:29], v[34:35], v[42:43], v[40:41]
	v_mul_f32_e32 v240, v245, v24
	v_mul_f32_e32 v241, v245, v25
	v_mul_f32_e32 v242, v245, v22
	v_mul_f32_e32 v243, v245, v23
	v_exp_f32_e32 v240, v240
	v_exp_f32_e32 v241, v241
	v_exp_f32_e32 v242, v242
	v_exp_f32_e32 v243, v243
	v_add_f32_e32 v240, 1.0, v240
	v_add_f32_e32 v241, 1.0, v241
	v_add_f32_e32 v242, 1.0, v242
	v_add_f32_e32 v243, 1.0, v243
	v_rcp_f32_e32 v240, v240
	v_rcp_f32_e32 v241, v241
	v_rcp_f32_e32 v242, v242
	v_rcp_f32_e32 v243, v243
	v_fma_f32 v240, v240, v246, v247
	v_fma_f32 v241, v241, v246, v247
	v_fma_f32 v242, v242, v246, v247
	v_fma_f32 v243, v243, v246, v247
	v_cndmask_b32_e64 v24, v240, v24, s[98:99]
	v_cndmask_b32_e64 v25, v241, v25, s[98:99]
	v_cndmask_b32_e64 v22, v242, v22, s[98:99]
	v_cndmask_b32_e64 v23, v243, v23, s[98:99]
	v_mul_f32_e32 v240, v245, v28
	v_mul_f32_e32 v241, v245, v29
	v_mul_f32_e32 v242, v245, v26
	v_mul_f32_e32 v243, v245, v27
	v_exp_f32_e32 v240, v240
	v_exp_f32_e32 v241, v241
	v_exp_f32_e32 v242, v242
	v_exp_f32_e32 v243, v243
	v_add_f32_e32 v240, 1.0, v240
	v_add_f32_e32 v241, 1.0, v241
	v_add_f32_e32 v242, 1.0, v242
	v_add_f32_e32 v243, 1.0, v243
	v_rcp_f32_e32 v240, v240
	v_rcp_f32_e32 v241, v241
	v_rcp_f32_e32 v242, v242
	v_rcp_f32_e32 v243, v243
	v_fma_f32 v240, v240, v246, v247
	v_fma_f32 v241, v241, v246, v247
	v_fma_f32 v242, v242, v246, v247
	v_fma_f32 v243, v243, v246, v247
	v_cndmask_b32_e64 v28, v240, v28, s[98:99]
	v_cndmask_b32_e64 v29, v241, v29, s[98:99]
	v_cndmask_b32_e64 v26, v242, v26, s[98:99]
	v_cndmask_b32_e64 v27, v243, v27, s[98:99]
	v_cvt_pk_bf16_f32 v30, v24, v25
	v_cvt_pk_bf16_f32 v31, v22, v23
	v_cvt_pk_bf16_f32 v32, v28, v29
	v_cvt_pk_bf16_f32 v33, v26, v27
	ds_write_b128 v208, v[30:33] offset:64
	global_load_dwordx4 v[22:25], v[20:21], off offset:3152
	global_load_dwordx4 v[26:29], v[0:1], off offset:3152
	global_load_dwordx4 v[30:33], v[118:119], off
	global_load_dwordx4 v[34:37], v[118:119], off offset:16
	v_cmp_lt_i32_e64 s[6:7], 0, v207
	s_waitcnt vmcnt(3)
; #define LAS __attribute__((address_space(3)))
; __device__ __forceinline__ unsigned pk2(float lo, float hi) { const f32x2c v = {lo, hi}; const bf16x2c b = __builtin_convertvector(v, bf16x2c); return __builtin_bit_cast(unsigned, b); }
; __device__ __forceinline__ float bflo(unsigned w) { return __uint_as_float(w << 16); }
; __device__ __forceinline__ float bfhi(unsigned w) { return __uint_as_float(w & 0xffff0000u); }
; __device__ __forceinline__ float fast_sigmoid(float x) { return __builtin_amdgcn_rcpf(1.f + __expf(-x)); }
; __device__ __forceinline__ f32x4 lerp4(const bf16_t* cur, const bf16_t* prv, bool first, const float* mu) {
;     const u32x2 a = *(const u32x2*)cur; u32x2 q = *(const u32x2*)prv; if (first) { q.x = 0u; q.y = 0u; }
;     const f32x4 m = *(const f32x4*)mu;
;     const f32x4 x = {bflo(a.x), bfhi(a.x), bflo(a.y), bfhi(a.y)}, y = {bflo(q.x), bfhi(q.x), bflo(q.y), bfhi(q.y)};
;     return x + (y - x) * m;
; }
; __device__ __forceinline__ void prep_rwkv_phase(const Params& p, LAS unsigned char* lds, int gw, int ngw, int wave, int lane) {
;     ...
;         for (int g8 = 0; g8 < 8; ++g8) {
;             const f32x4 x0 = lerp4(pr + g8 * 8, pp + g8 * 8, first, p.mu + 1536 + cq * 64 + g8 * 8);
;             const f32x4 x1 = lerp4(pr + g8 * 8 + 4, pp + g8 * 8 + 4, first, p.mu + 1536 + cq * 64 + g8 * 8 + 4);
;             float v[8] = {x0.x, x0.y, x0.z, x0.w, x1.x, x1.y, x1.z, x1.w};
; #pragma unroll
;             for (int e = 0; e < 8; ++e) { if (cq == 0) v[e] = 1.f - 2.f * __builtin_amdgcn_rcpf(__expf(2.f * v[e]) + 1.f); else if (cq >= 2) v[e] = fast_sigmoid(v[e]); }
;             u32x4 w; w.x = pk2(v[0], v[1]); w.y = pk2(v[2], v[3]); w.z = pk2(v[4], v[5]); w.w = pk2(v[6], v[7]);
;             *(LAS u32x4*)(act + tk * 264 + cq * 64 + g8 * 8) = w;
;         }
	v_cndmask_b32_e64 v2, v23, 0, vcc
	v_cndmask_b32_e64 v42, v22, 0, vcc
	v_cndmask_b32_e64 v25, v25, 0, vcc
	v_cndmask_b32_e64 v24, v24, 0, vcc
	s_waitcnt vmcnt(2)
	v_lshlrev_b32_e32 v38, 16, v26
	v_and_b32_e32 v39, 0xffff0000, v26
	v_lshlrev_b32_e32 v22, 16, v27
	v_and_b32_e32 v23, 0xffff0000, v27
	v_lshlrev_b32_e32 v40, 16, v28
	v_and_b32_e32 v41, 0xffff0000, v28
	v_lshlrev_b32_e32 v26, 16, v29
	v_and_b32_e32 v27, 0xffff0000, v29
	v_lshlrev_b32_e32 v28, 16, v42
	v_and_b32_e32 v29, 0xffff0000, v42
	v_lshlrev_b32_e32 v42, 16, v2
	v_and_b32_e32 v2, 0xffff0000, v2
	v_lshlrev_b32_e32 v44, 16, v24
	v_and_b32_e32 v43, 0xffff0000, v24
	v_lshlrev_b32_e32 v46, 16, v25
	v_and_b32_e32 v45, 0xffff0000, v25
	v_sub_f32_e32 v25, v29, v39
	v_sub_f32_e32 v24, v28, v38
	v_sub_f32_e32 v29, v2, v23
	v_sub_f32_e32 v28, v42, v22
	v_sub_f32_e32 v43, v43, v41
	v_sub_f32_e32 v42, v44, v40
	v_sub_f32_e32 v45, v45, v27
	v_sub_f32_e32 v44, v46, v26
	s_waitcnt vmcnt(1)
	v_pk_fma_f32 v[22:23], v[32:33], v[28:29], v[22:23]
	v_pk_fma_f32 v[24:25], v[30:31], v[24:25], v[38:39]
	s_waitcnt vmcnt(0)
	v_pk_fma_f32 v[26:27], v[36:37], v[44:45], v[26:27]
	v_pk_fma_f32 v[28:29], v[34:35], v[42:43], v[40:41]
	v_mul_f32_e32 v240, v245, v24
	v_mul_f32_e32 v241, v245, v25
	v_mul_f32_e32 v242, v245, v22
	v_mul_f32_e32 v243, v245, v23
	v_exp_f32_e32 v240, v240
	v_exp_f32_e32 v241, v241
	v_exp_f32_e32 v242, v242
	v_exp_f32_e32 v243, v243
	v_add_f32_e32 v240, 1.0, v240
	v_add_f32_e32 v241, 1.0, v241
	v_add_f32_e32 v242, 1.0, v242
	v_add_f32_e32 v243, 1.0, v243
	v_rcp_f32_e32 v240, v240
	v_rcp_f32_e32 v241, v241
	v_rcp_f32_e32 v242, v242
	v_rcp_f32_e32 v243, v243
	v_fma_f32 v240, v240, v246, v247
	v_fma_f32 v241, v241, v246, v247
	v_fma_f32 v242, v242, v246, v247
	v_fma_f32 v243, v243, v246, v247
	v_cndmask_b32_e64 v24, v240, v24, s[98:99]
	v_cndmask_b32_e64 v25, v241, v25, s[98:99]
	v_cndmask_b32_e64 v22, v242, v22, s[98:99]
	v_cndmask_b32_e64 v23, v243, v23, s[98:99]
	v_mul_f32_e32 v240, v245, v28
	v_mul_f32_e32 v241, v245, v29
	v_mul_f32_e32 v242, v245, v26
	v_mul_f32_e32 v243, v245, v27
	v_exp_f32_e32 v240, v240
	v_exp_f32_e32 v241, v241
	v_exp_f32_e32 v242, v242
	v_exp_f32_e32 v243, v243
	v_add_f32_e32 v240, 1.0, v240
	v_add_f32_e32 v241, 1.0, v241
	v_add_f32_e32 v242, 1.0, v242
	v_add_f32_e32 v243, 1.0, v243
	v_rcp_f32_e32 v240, v240
	v_rcp_f32_e32 v241, v241
	v_rcp_f32_e32 v242, v242
	v_rcp_f32_e32 v243, v243
	v_fma_f32 v240, v240, v246, v247
	v_fma_f32 v241, v241, v246, v247
	v_fma_f32 v242, v242, v246, v247
	v_fma_f32 v243, v243, v246, v247
	v_cndmask_b32_e64 v28, v240, v28, s[98:99]
	v_cndmask_b32_e64 v29, v241, v29, s[98:99]
	v_cndmask_b32_e64 v26, v242, v26, s[98:99]
	v_cndmask_b32_e64 v27, v243, v27, s[98:99]
	v_cvt_pk_bf16_f32 v30, v24, v25
	v_cvt_pk_bf16_f32 v31, v22, v23
	v_cvt_pk_bf16_f32 v32, v28, v29
	v_cvt_pk_bf16_f32 v33, v26, v27
	ds_write_b128 v208, v[30:33] offset:80
	global_load_dwordx4 v[22:25], v[20:21], off offset:3168
	global_load_dwordx4 v[26:29], v[0:1], off offset:3168
	global_load_dwordx4 v[30:33], v[120:121], off
	global_load_dwordx4 v[34:37], v[120:121], off offset:16
	v_cmp_lt_i32_e64 s[6:7], 0, v207
	s_waitcnt vmcnt(3)
	v_cndmask_b32_e64 v2, v23, 0, vcc
	v_cndmask_b32_e64 v42, v22, 0, vcc
	v_cndmask_b32_e64 v25, v25, 0, vcc
	v_cndmask_b32_e64 v24, v24, 0, vcc
	s_waitcnt vmcnt(2)
	v_lshlrev_b32_e32 v38, 16, v26
	v_and_b32_e32 v39, 0xffff0000, v26
	v_lshlrev_b32_e32 v22, 16, v27
	v_and_b32_e32 v23, 0xffff0000, v27
	v_lshlrev_b32_e32 v40, 16, v28
	v_and_b32_e32 v41, 0xffff0000, v28
	v_lshlrev_b32_e32 v26, 16, v29
	v_and_b32_e32 v27, 0xffff0000, v29
	v_lshlrev_b32_e32 v28, 16, v42
	v_and_b32_e32 v29, 0xffff0000, v42
	v_lshlrev_b32_e32 v42, 16, v2
	v_and_b32_e32 v2, 0xffff0000, v2
	v_lshlrev_b32_e32 v44, 16, v24
	v_and_b32_e32 v43, 0xffff0000, v24
	v_lshlrev_b32_e32 v46, 16, v25
	v_and_b32_e32 v45, 0xffff0000, v25
	v_sub_f32_e32 v25, v29, v39
	v_sub_f32_e32 v24, v28, v38
	v_sub_f32_e32 v29, v2, v23
	v_sub_f32_e32 v28, v42, v22
	v_sub_f32_e32 v43, v43, v41
	v_sub_f32_e32 v42, v44, v40
	v_sub_f32_e32 v45, v45, v27
	v_sub_f32_e32 v44, v46, v26
	s_waitcnt vmcnt(1)
	v_pk_fma_f32 v[22:23], v[32:33], v[28:29], v[22:23]
	v_pk_fma_f32 v[24:25], v[30:31], v[24:25], v[38:39]
	s_waitcnt vmcnt(0)
; #define LAS __attribute__((address_space(3)))
; __device__ __forceinline__ unsigned pk2(float lo, float hi) { const f32x2c v = {lo, hi}; const bf16x2c b = __builtin_convertvector(v, bf16x2c); return __builtin_bit_cast(unsigned, b); }
; __device__ __forceinline__ float bflo(unsigned w) { return __uint_as_float(w << 16); }
; __device__ __forceinline__ float bfhi(unsigned w) { return __uint_as_float(w & 0xffff0000u); }
; __device__ __forceinline__ float fast_sigmoid(float x) { return __builtin_amdgcn_rcpf(1.f + __expf(-x)); }
; __device__ __forceinline__ f32x4 lerp4(const bf16_t* cur, const bf16_t* prv, bool first, const float* mu) {
;     const u32x2 a = *(const u32x2*)cur; u32x2 q = *(const u32x2*)prv; if (first) { q.x = 0u; q.y = 0u; }
;     const f32x4 m = *(const f32x4*)mu;
;     const f32x4 x = {bflo(a.x), bfhi(a.x), bflo(a.y), bfhi(a.y)}, y = {bflo(q.x), bfhi(q.x), bflo(q.y), bfhi(q.y)};
;     return x + (y - x) * m;
; }
; __device__ __forceinline__ void prep_rwkv_phase(const Params& p, LAS unsigned char* lds, int gw, int ngw, int wave, int lane) {
;     ...
;         for (int g8 = 0; g8 < 8; ++g8) {
;             const f32x4 x0 = lerp4(pr + g8 * 8, pp + g8 * 8, first, p.mu + 1536 + cq * 64 + g8 * 8);
;             const f32x4 x1 = lerp4(pr + g8 * 8 + 4, pp + g8 * 8 + 4, first, p.mu + 1536 + cq * 64 + g8 * 8 + 4);
;             float v[8] = {x0.x, x0.y, x0.z, x0.w, x1.x, x1.y, x1.z, x1.w};
; #pragma unroll
;             for (int e = 0; e < 8; ++e) { if (cq == 0) v[e] = 1.f - 2.f * __builtin_amdgcn_rcpf(__expf(2.f * v[e]) + 1.f); else if (cq >= 2) v[e] = fast_sigmoid(v[e]); }
;             u32x4 w; w.x = pk2(v[0], v[1]); w.y = pk2(v[2], v[3]); w.z = pk2(v[4], v[5]); w.w = pk2(v[6], v[7]);
;             *(LAS u32x4*)(act + tk * 264 + cq * 64 + g8 * 8) = w;
;         }
;     }
;     prep_w_store(lds, tid, wreg);
	v_pk_fma_f32 v[26:27], v[36:37], v[44:45], v[26:27]
	v_pk_fma_f32 v[28:29], v[34:35], v[42:43], v[40:41]
	v_mul_f32_e32 v240, v245, v24
	v_mul_f32_e32 v241, v245, v25
	v_mul_f32_e32 v242, v245, v22
	v_mul_f32_e32 v243, v245, v23
	v_exp_f32_e32 v240, v240
	v_exp_f32_e32 v241, v241
	v_exp_f32_e32 v242, v242
	v_exp_f32_e32 v243, v243
	v_add_f32_e32 v240, 1.0, v240
	v_add_f32_e32 v241, 1.0, v241
	v_add_f32_e32 v242, 1.0, v242
	v_add_f32_e32 v243, 1.0, v243
	v_rcp_f32_e32 v240, v240
	v_rcp_f32_e32 v241, v241
	v_rcp_f32_e32 v242, v242
	v_rcp_f32_e32 v243, v243
	v_fma_f32 v240, v240, v246, v247
	v_fma_f32 v241, v241, v246, v247
	v_fma_f32 v242, v242, v246, v247
	v_fma_f32 v243, v243, v246, v247
	v_cndmask_b32_e64 v24, v240, v24, s[98:99]
	v_cndmask_b32_e64 v25, v241, v25, s[98:99]
	v_cndmask_b32_e64 v22, v242, v22, s[98:99]
	v_cndmask_b32_e64 v23, v243, v23, s[98:99]
	v_mul_f32_e32 v240, v245, v28
	v_mul_f32_e32 v241, v245, v29
	v_mul_f32_e32 v242, v245, v26
	v_mul_f32_e32 v243, v245, v27
	v_exp_f32_e32 v240, v240
	v_exp_f32_e32 v241, v241
	v_exp_f32_e32 v242, v242
	v_exp_f32_e32 v243, v243
	v_add_f32_e32 v240, 1.0, v240
	v_add_f32_e32 v241, 1.0, v241
	v_add_f32_e32 v242, 1.0, v242
	v_add_f32_e32 v243, 1.0, v243
	v_rcp_f32_e32 v240, v240
	v_rcp_f32_e32 v241, v241
	v_rcp_f32_e32 v242, v242
	v_rcp_f32_e32 v243, v243
	v_fma_f32 v240, v240, v246, v247
	v_fma_f32 v241, v241, v246, v247
	v_fma_f32 v242, v242, v246, v247
	v_fma_f32 v243, v243, v246, v247
	v_cndmask_b32_e64 v28, v240, v28, s[98:99]
	v_cndmask_b32_e64 v29, v241, v29, s[98:99]
	v_cndmask_b32_e64 v26, v242, v26, s[98:99]
	v_cndmask_b32_e64 v27, v243, v27, s[98:99]
	v_cvt_pk_bf16_f32 v30, v24, v25
	v_cvt_pk_bf16_f32 v31, v22, v23
	v_cvt_pk_bf16_f32 v32, v28, v29
	v_cvt_pk_bf16_f32 v33, v26, v27
	ds_write_b128 v208, v[30:33] offset:96
	global_load_dwordx4 v[20:23], v[20:21], off offset:3184
	s_nop 0
	global_load_dwordx4 v[24:27], v[0:1], off offset:3184
	global_load_dwordx4 v[28:31], v[122:123], off
	global_load_dwordx4 v[32:35], v[122:123], off offset:16
	s_waitcnt vmcnt(3)
	v_cndmask_b32_e64 v2, v21, 0, vcc
	v_cndmask_b32_e64 v36, v20, 0, vcc
	v_cndmask_b32_e64 v37, v23, 0, vcc
	v_cndmask_b32_e64 v38, v22, 0, vcc
	s_waitcnt vmcnt(2)
	v_lshlrev_b32_e32 v20, 16, v24
	v_and_b32_e32 v21, 0xffff0000, v24
	v_lshlrev_b32_e32 v0, 16, v25
	v_and_b32_e32 v1, 0xffff0000, v25
	v_lshlrev_b32_e32 v24, 16, v26
	v_and_b32_e32 v25, 0xffff0000, v26
	v_lshlrev_b32_e32 v22, 16, v27
	v_and_b32_e32 v23, 0xffff0000, v27
	v_lshlrev_b32_e32 v26, 16, v36
	v_and_b32_e32 v27, 0xffff0000, v36
	v_lshlrev_b32_e32 v36, 16, v2
	v_and_b32_e32 v2, 0xffff0000, v2
	v_lshlrev_b32_e32 v40, 16, v38
	v_and_b32_e32 v38, 0xffff0000, v38
	v_lshlrev_b32_e32 v42, 16, v37
	v_and_b32_e32 v41, 0xffff0000, v37
	v_sub_f32_e32 v27, v27, v21
	v_sub_f32_e32 v26, v26, v20
	v_sub_f32_e32 v37, v2, v1
	v_sub_f32_e32 v36, v36, v0
	v_sub_f32_e32 v39, v38, v25
	v_sub_f32_e32 v38, v40, v24
	v_sub_f32_e32 v41, v41, v23
	v_sub_f32_e32 v40, v42, v22
	s_waitcnt vmcnt(1)
	v_pk_fma_f32 v[0:1], v[30:31], v[36:37], v[0:1]
	v_pk_fma_f32 v[20:21], v[28:29], v[26:27], v[20:21]
	s_waitcnt vmcnt(0)
	v_pk_fma_f32 v[22:23], v[34:35], v[40:41], v[22:23]
	v_pk_fma_f32 v[24:25], v[32:33], v[38:39], v[24:25]
	v_mul_f32_e32 v240, v245, v20
	v_mul_f32_e32 v241, v245, v21
	v_mul_f32_e32 v242, v245, v0
	v_mul_f32_e32 v243, v245, v1
	v_exp_f32_e32 v240, v240
	v_exp_f32_e32 v241, v241
	v_exp_f32_e32 v242, v242
	v_exp_f32_e32 v243, v243
	v_add_f32_e32 v240, 1.0, v240
	v_add_f32_e32 v241, 1.0, v241
	v_add_f32_e32 v242, 1.0, v242
	v_add_f32_e32 v243, 1.0, v243
	v_rcp_f32_e32 v240, v240
	v_rcp_f32_e32 v241, v241
	v_rcp_f32_e32 v242, v242
	v_rcp_f32_e32 v243, v243
	v_fma_f32 v240, v240, v246, v247
	v_fma_f32 v241, v241, v246, v247
	v_fma_f32 v242, v242, v246, v247
	v_fma_f32 v243, v243, v246, v247
	v_cndmask_b32_e64 v20, v240, v20, s[98:99]
	v_cndmask_b32_e64 v21, v241, v21, s[98:99]
	v_cndmask_b32_e64 v0, v242, v0, s[98:99]
	v_cndmask_b32_e64 v1, v243, v1, s[98:99]
	v_mul_f32_e32 v240, v245, v24
	v_mul_f32_e32 v241, v245, v25
	v_mul_f32_e32 v242, v245, v22
	v_mul_f32_e32 v243, v245, v23
	v_exp_f32_e32 v240, v240
	v_exp_f32_e32 v241, v241
	v_exp_f32_e32 v242, v242
	v_exp_f32_e32 v243, v243
	v_add_f32_e32 v240, 1.0, v240
	v_add_f32_e32 v241, 1.0, v241
	v_add_f32_e32 v242, 1.0, v242
	v_add_f32_e32 v243, 1.0, v243
	v_rcp_f32_e32 v240, v240
	v_rcp_f32_e32 v241, v241
	v_rcp_f32_e32 v242, v242
	v_rcp_f32_e32 v243, v243
	v_fma_f32 v240, v240, v246, v247
	v_fma_f32 v241, v241, v246, v247
	v_fma_f32 v242, v242, v246, v247
	v_fma_f32 v243, v243, v246, v247
	v_cndmask_b32_e64 v24, v240, v24, s[98:99]
	v_cndmask_b32_e64 v25, v241, v25, s[98:99]
	v_cndmask_b32_e64 v22, v242, v22, s[98:99]
	v_cndmask_b32_e64 v23, v243, v23, s[98:99]
	v_cvt_pk_bf16_f32 v26, v20, v21
	v_cvt_pk_bf16_f32 v27, v0, v1
	v_cvt_pk_bf16_f32 v28, v24, v25
	v_cvt_pk_bf16_f32 v29, v22, v23
	ds_write_b128 v208, v[26:29] offset:112

; #define LAS __attribute__((address_space(3)))
; #define lane (lane_now())
; __device__ __forceinline__ void attn_unit(const Params& p, const LAS float* bl, LAS bf16_t* stg, int unit, int lane) {
;     const bf16_t* PB = (const bf16_t*)(p.ws + WS_PB); bf16_t* MIX = (bf16_t*)(p.ws + WS_MIX);
;     const int half = unit & 1, cq = (unit >> 1) & 127, bh = unit >> 8, b = bh >> 3, h = bh & 7;
;     const int r32 = lane & 31, hi = lane >> 5;
;     const unsigned loff = (unsigned)(((lane >> 3) * NPB + (lane & 7) * 8) * 2);
;     ...
;     const size_t tok0 = (size_t)b * SEQ;
;     const bf16_t* qblk = PB + (tok0 + cq * 64) * NPB + h * 64;
;     bf16x8 qf[4];
; #pragma unroll
;     for (int d0 = 0; d0 < 4; ++d0) qf[d0] = __builtin_bit_cast(bf16x8, *FRAGP(qblk, half * 4 + d0));
;     f32x16 o0 = {}, o1 = {}; float lsum = 0.f;
;     const LAS float* blh = bl + h * 513;
;     const int qi = half * 32 + r32;
;     u32x4 kc[8], vc[8];
;     const int dl0 = (cq < 8 ? cq : 8);
;     { const bf16_t* kblk = PB + (tok0 + (size_t)(cq - dl0) * 64) * NPB + 512 + h * 64;
; #pragma unroll
;       for (int f = 0; f < 8; ++f) kc[f] = *FRAGP(kblk, f); }
; __global__ void __launch_bounds__(512, 2) mega_fwd(Params p) {
;     ...
;             const unsigned qx = (myx + qi) & 7u; unsigned* qctr = qbase + 64 * qx;
;             for (;;) {
;                 unsigned u = 0u;
;                 if (lane8a == 0) u = __hip_atomic_fetch_add(qctr, 1u, __ATOMIC_RELAXED, __HIP_MEMORY_SCOPE_AGENT);
;                 u = (unsigned)__builtin_amdgcn_readfirstlane((int)u);
;                 if (u >= 4u * 256u) break;
;                 attn_unit(p, bl, (LAS bf16_t*)(lds + 73728 + wave * (32 * MS * 2)), (int)(((qx + 8u * (u >> 8)) << 8) | (u & 255u)), lane8a);
.LBB0_1029:
	s_or_b64 exec, exec, s[12:13]
	v_readfirstlane_b32 s0, v0
	s_cmpk_gt_u32 s0, 0x3ff
	s_mov_b64 s[12:13], -1
	s_cbranch_scc1 .LBB0_1024
	s_and_b32 s12, s0, 1
	s_bfe_u32 s14, s0, 0x70001
	s_lshl_b32 s0, s0, 5
	s_and_b32 s13, s0, 0x6000
	s_lshl_b32 s0, s14, 6
	s_or_b32 s11, s0, s13
	s_mul_i32 s0, s11, 0xc00
	v_lshl_add_u64 v[0:1], v[158:159], 0, s[0:1]
	s_mul_i32 s0, s12, 0x18000
	v_lshl_add_u64 v[0:1], v[0:1], 0, s[0:1]
	v_add_co_u32_e32 v2, vcc, 0x6000, v0
	s_min_u32 s16, s14, 8
	s_nop 0
	v_addc_co_u32_e32 v3, vcc, 0, v1, vcc
	global_load_dwordx4 v[64:67], v[0:1], off
	global_load_dwordx4 v[68:71], v[2:3], off
	v_add_co_u32_e32 v2, vcc, 0xc000, v0
	s_lshl_b32 s0, s12, 5
	s_nop 0
	v_addc_co_u32_e32 v3, vcc, 0, v1, vcc
	s_sub_i32 s12, s14, s16
	v_add_co_u32_e32 v0, vcc, s20, v0
	s_lshl_b32 s12, s12, 6
	s_nop 0
	v_addc_co_u32_e32 v1, vcc, 0, v1, vcc
	s_add_i32 s12, s12, s13
	global_load_dwordx4 v[72:75], v[2:3], off
	global_load_dwordx4 v[76:79], v[0:1], off
	v_mad_i64_i32 v[0:1], s[12:13], s12, v175, v[158:159]
	v_add_co_u32_e32 v2, vcc, s21, v0
	s_lshl_b32 s12, s16, 8
	s_nop 0
	v_addc_co_u32_e32 v3, vcc, 0, v1, vcc
	global_load_dwordx4 v[80:83], v[0:1], off offset:1024
	global_load_dwordx4 v[84:87], v[2:3], off offset:1024
	v_add_co_u32_e32 v2, vcc, s23, v0
	s_add_i32 s12, s38, s12
	s_nop 0
	v_addc_co_u32_e32 v3, vcc, 0, v1, vcc
	v_add_co_u32_e32 v4, vcc, s20, v0
	s_cmp_lt_u32 s14, 8
	s_nop 0
	v_addc_co_u32_e32 v5, vcc, 0, v1, vcc
	global_load_dwordx4 v[88:91], v[2:3], off offset:1024
	global_load_dwordx4 v[92:95], v[4:5], off offset:1024
	v_add_co_u32_e32 v2, vcc, s22, v0
	v_mov_b32_e32 v209, 0
	s_nop 0
	v_addc_co_u32_e32 v3, vcc, 0, v1, vcc
	v_add_co_u32_e32 v4, vcc, s24, v0
	v_mov_b32_e32 v6, v209
	s_nop 0
	v_addc_co_u32_e32 v5, vcc, 0, v1, vcc
	global_load_dwordx4 v[96:99], v[2:3], off offset:1024
	global_load_dwordx4 v[100:103], v[4:5], off offset:1024
	v_add_co_u32_e32 v2, vcc, s25, v0
	v_mov_b32_e32 v4, v209
	s_nop 0
	v_addc_co_u32_e32 v3, vcc, 0, v1, vcc
	v_add_co_u32_e32 v0, vcc, s26, v0
	v_mov_b32_e32 v5, v209
	s_nop 0
	v_addc_co_u32_e32 v1, vcc, 0, v1, vcc
	global_load_dwordx4 v[104:107], v[2:3], off offset:1024
	global_load_dwordx4 v[108:111], v[0:1], off offset:1024
	v_or_b32_e32 v0, s0, v167
	v_or_b32_e32 v0, 0x200, v0
	v_sub_u32_e32 v1, v0, v168
	v_min_i32_e32 v2, 0x200, v1
	v_min_i32_e32 v3, 0x220, v1
	v_lshl_add_u32 v176, v2, 2, s37
	v_lshl_add_u32 v2, v3, 2, s37
	v_add_u32_e32 v177, 0xffffff80, v2
	v_add_u32_e32 v2, v0, v169
	v_min_i32_e32 v3, 0x200, v2
	v_min_i32_e32 v2, 0x220, v2
	v_lshl_add_u32 v2, v2, 2, s37
	v_add_u32_e32 v179, 0xffffff80, v2
	v_sub_u32_e32 v2, v0, v170
	v_lshl_add_u32 v178, v3, 2, s37
	v_min_i32_e32 v3, 0x200, v2
	v_min_i32_e32 v2, 0x220, v2
	v_lshl_add_u32 v2, v2, 2, s37
	v_sub_u32_e32 v0, v0, v171
	v_lshl_add_u32 v180, v3, 2, s37
	v_add_u32_e32 v181, 0xffffff80, v2
	v_min_i32_e32 v2, 0x200, v0
	v_min_i32_e32 v3, 0x220, v0
	v_lshl_add_u32 v182, v2, 2, s37
	v_lshl_add_u32 v2, v3, 2, s37
	v_add_u32_e32 v183, 0xffffff80, v2
	v_add_u32_e32 v2, -8, v1
	v_min_i32_e32 v3, 0x200, v2
	v_min_i32_e32 v2, 0x220, v2
	v_lshl_add_u32 v2, v2, 2, s37
	v_add_u32_e32 v185, 0xffffff80, v2
	v_add_u32_e32 v2, -9, v1
	v_lshl_add_u32 v184, v3, 2, s37
	v_min_i32_e32 v3, 0x200, v2
	v_min_i32_e32 v2, 0x220, v2
	v_lshl_add_u32 v2, v2, 2, s37
	v_add_u32_e32 v187, 0xffffff80, v2
	v_add_u32_e32 v2, -10, v1
	v_lshl_add_u32 v186, v3, 2, s37
	v_min_i32_e32 v3, 0x200, v2
	v_min_i32_e32 v2, 0x220, v2
	v_lshl_add_u32 v2, v2, 2, s37
	v_add_u32_e32 v189, 0xffffff80, v2
	v_add_u32_e32 v2, -8, v0
	v_lshl_add_u32 v188, v3, 2, s37
	v_min_i32_e32 v3, 0x200, v2
	v_min_i32_e32 v2, 0x220, v2
	v_lshl_add_u32 v2, v2, 2, s37
	v_add_u32_e32 v191, 0xffffff80, v2
	v_add_u32_e32 v2, -16, v1
	v_lshl_add_u32 v190, v3, 2, s37
	v_min_i32_e32 v3, 0x200, v2
	v_min_i32_e32 v2, 0x220, v2
	v_lshl_add_u32 v2, v2, 2, s37
	v_add_u32_e32 v193, 0xffffff80, v2
	v_subrev_u32_e32 v2, 17, v1
	v_lshl_add_u32 v192, v3, 2, s37
	v_min_i32_e32 v3, 0x200, v2
	v_min_i32_e32 v2, 0x220, v2
	v_lshl_add_u32 v2, v2, 2, s37
	v_add_u32_e32 v195, 0xffffff80, v2
	v_subrev_u32_e32 v2, 18, v1
	v_lshl_add_u32 v194, v3, 2, s37
	v_min_i32_e32 v3, 0x200, v2
	v_min_i32_e32 v2, 0x220, v2
	v_lshl_add_u32 v2, v2, 2, s37
	v_add_u32_e32 v197, 0xffffff80, v2
	v_add_u32_e32 v2, -16, v0
	v_lshl_add_u32 v196, v3, 2, s37
	v_min_i32_e32 v3, 0x200, v2
	v_min_i32_e32 v2, 0x220, v2
	v_lshl_add_u32 v2, v2, 2, s37
	v_add_u32_e32 v199, 0xffffff80, v2
	v_subrev_u32_e32 v2, 24, v1
	v_lshl_add_u32 v198, v3, 2, s37
	v_min_i32_e32 v3, 0x200, v2
	v_min_i32_e32 v2, 0x220, v2
	v_lshl_add_u32 v2, v2, 2, s37
	v_add_u32_e32 v201, 0xffffff80, v2
	v_subrev_u32_e32 v2, 25, v1
	v_lshl_add_u32 v200, v3, 2, s37
	v_min_i32_e32 v3, 0x200, v2
	v_min_i32_e32 v2, 0x220, v2
	v_lshl_add_u32 v2, v2, 2, s37
	v_subrev_u32_e32 v1, 26, v1
	v_add_u32_e32 v203, 0xffffff80, v2
	v_min_i32_e32 v2, 0x200, v1
	v_min_i32_e32 v1, 0x220, v1
	v_lshl_add_u32 v1, v1, 2, s37
	v_subrev_u32_e32 v0, 24, v0
	v_add_u32_e32 v205, 0xffffff80, v1
	v_min_i32_e32 v1, 0x200, v0
	v_min_i32_e32 v0, 0x220, v0
	v_lshl_add_u32 v0, v0, 2, s37
	v_add_u32_e32 v207, 0xffffff80, v0
	v_add_u32_e32 v0, s0, v173
	v_lshl_add_u32 v208, v0, 2, s12
	s_cselect_b32 s12, s14, 8
	s_mul_i32 s17, s12, 0x30000
	s_lshl_b32 s12, s12, 6
	s_sub_i32 s12, s11, s12
	v_mad_i64_i32 v[162:163], s[12:13], s12, v175, v[160:161]
	v_lshl_add_u32 v202, v3, 2, s37
	v_lshl_add_u32 v204, v2, 2, s37
	v_lshl_add_u32 v206, v1, 2, s37
	v_readfirstlane_b32 s98, v162
	v_readfirstlane_b32 s99, v163
	s_nop 1
	v_subrev_u32_e32 v226, s98, v162
	v_add_u32_e32 v227, 0x6000, v226
	v_add_u32_e32 v228, 0xc000, v226
	v_add_u32_e32 v229, 0x12000, v226
	v_add_u32_e32 v230, 0x18000, v226
	v_add_u32_e32 v231, 0x1e000, v226
	v_add_u32_e32 v232, 0x24000, v226
	v_add_u32_e32 v233, 0x2a000, v226
	s_add_u32 s39, s17, 0xfff40000
	s_add_u32 s40, s17, 0x30000
	s_mov_b64 s[12:13], 0
	v_mov_b32_e32 v0, 0
	v_mov_b32_e32 v1, v209
	v_mov_b32_e32 v2, v209
	v_mov_b32_e32 v3, v209
	v_mov_b32_e32 v7, v209
	v_mov_b32_e32 v8, v209
	v_mov_b32_e32 v9, v209
	v_mov_b32_e32 v10, v209
	v_mov_b32_e32 v11, v209
	v_mov_b32_e32 v12, v209
	v_mov_b32_e32 v13, v209
	v_mov_b32_e32 v14, v209
	v_mov_b32_e32 v15, v209
	v_mov_b32_e32 v16, 0
	v_mov_b32_e32 v17, v209
	v_mov_b32_e32 v18, v209
	v_mov_b32_e32 v19, v209
	v_mov_b32_e32 v20, v209
	v_mov_b32_e32 v21, v209
	v_mov_b32_e32 v22, v209
	v_mov_b32_e32 v23, v209
	v_mov_b32_e32 v24, v209
	v_mov_b32_e32 v25, v209
	v_mov_b32_e32 v26, v209
	v_mov_b32_e32 v27, v209
	v_mov_b32_e32 v28, v209
	v_mov_b32_e32 v29, v209
	v_mov_b32_e32 v30, v209
	v_mov_b32_e32 v31, v209
	s_branch .LBB0_1032
; __device__ __forceinline__ void attn_unit(const Params& p, const LAS float* bl, LAS bf16_t* stg, int unit, int lane) {
;     ...
;         const size_t krow0 = tok0 + (size_t)(cq - dlt) * 64;
;         { const bf16_t* vblk = PB + krow0 * NPB + 1024 + h * 64;
; #pragma unroll
;           for (int f = 0; f < 8; ++f) vc[f] = *FRAGP(vblk, f); }
;         __builtin_amdgcn_sched_barrier(0);
;         f32x16 s0, s1;
;         if (dlt >= 5) {
;             const float bc = blh[512];
; #pragma unroll
;             for (int r = 0; r < 16; ++r) { s0[r] = bc; s1[r] = bc; }
;         } else if (dlt == 4) {
;             const int base = dlt * 64 + qi + 256;
; #pragma unroll
;             for (int r = 0; r < 16; ++r) { const int kv = crow(r, hi); int i0 = base - kv, i1 = base - kv - 32; i0 = i0 > 512 ? 512 : i0; i1 = i1 > 512 ? 512 : i1; s0[r] = blh[i0]; s1[r] = blh[i1]; }
;         } else {
;             const LAS float* bp = blh + (dlt * 64 + qi + 256 - 4 * hi - 59);
; #pragma unroll
;             for (int r = 0; r < 16; ++r) { const int k0 = (r & 3) + 8 * (r >> 2); s0[r] = bp[59 - k0]; s1[r] = bp[27 - k0]; }
;         }
; #pragma unroll
;         for (int d0 = 0; d0 < 4; ++d0) {
;             s0 = __builtin_amdgcn_mfma_f32_32x32x16_bf16(__builtin_bit_cast(bf16x8, kc[d0]), qf[d0], s0, 0, 0, 0);
;             s1 = __builtin_amdgcn_mfma_f32_32x32x16_bf16(__builtin_bit_cast(bf16x8, kc[4 + d0]), qf[d0], s1, 0, 0, 0);
;         }
;         if (dlt > 0) { const bf16_t* kblk = PB + (krow0 + 64) * NPB + 512 + h * 64;
; #pragma unroll
;           for (int f = 0; f < 8; ++f) kc[f] = *FRAGP(kblk, f); }
;         __builtin_amdgcn_sched_barrier(0);
; #pragma unroll
;         for (int r = 0; r < 16; ++r) { s0[r] = __builtin_amdgcn_exp2f(s0[r]); s1[r] = __builtin_amdgcn_exp2f(s1[r]); }
;         float ls = 0.f;
; #pragma unroll
;         for (int r = 0; r < 16; ++r) ls += s0[r] + s1[r];
;         lsum += ls;
;         u32x4 pf[4];
;         pf[0] = (u32x4){pk2(s0[0], s0[1]), pk2(s0[2], s0[3]), pk2(s0[4], s0[5]), pk2(s0[6], s0[7])};
;         pf[1] = (u32x4){pk2(s0[8], s0[9]), pk2(s0[10], s0[11]), pk2(s0[12], s0[13]), pk2(s0[14], s0[15])};
;         pf[2] = (u32x4){pk2(s1[0], s1[1]), pk2(s1[2], s1[3]), pk2(s1[4], s1[5]), pk2(s1[6], s1[7])};
;         pf[3] = (u32x4){pk2(s1[8], s1[9]), pk2(s1[10], s1[11]), pk2(s1[12], s1[13]), pk2(s1[14], s1[15])};
; #pragma unroll
.LBB0_1031:
	s_nop 8
	v_exp_f32_e32 v164, v48
	v_exp_f32_e32 v210, v49
	v_exp_f32_e32 v212, v50
	v_exp_f32_e32 v214, v51
	v_exp_f32_e32 v49, v52
	v_exp_f32_e32 v51, v36
	v_exp_f32_e32 v48, v53
	v_exp_f32_e32 v50, v37
	v_exp_f32_e32 v37, v54
	v_exp_f32_e32 v36, v55
	v_exp_f32_e32 v213, v34
	v_exp_f32_e32 v215, v35
	v_exp_f32_e32 v55, v40
	v_exp_f32_e32 v54, v41
	v_exp_f32_e32 v41, v58
	v_exp_f32_e32 v40, v59
	v_exp_f32_e32 v59, v44
	v_exp_f32_e32 v58, v45
	v_exp_f32_e32 v45, v62
	v_exp_f32_e32 v44, v63
	v_exp_f32_e32 v165, v32
	v_exp_f32_e32 v211, v33
	v_cvt_pk_bf16_f32 v32, v164, v210
	v_cvt_pk_bf16_f32 v33, v212, v214
	v_cvt_pk_bf16_f32 v34, v49, v48
	v_cvt_pk_bf16_f32 v35, v37, v36
	v_exp_f32_e32 v53, v38
	v_exp_f32_e32 v52, v39
	s_waitcnt vmcnt(7)
	v_mfma_f32_32x32x16_bf16 v[0:15], v[136:139], v[32:35], v[0:15]
	v_exp_f32_e32 v39, v56
	v_exp_f32_e32 v38, v57
	v_exp_f32_e32 v57, v42
	v_exp_f32_e32 v56, v43
	v_exp_f32_e32 v43, v60
	v_exp_f32_e32 v42, v61
	v_exp_f32_e32 v61, v46
	s_waitcnt vmcnt(3)
	v_mfma_f32_32x32x16_bf16 v[16:31], v[140:143], v[32:35], v[16:31]
	v_add_f32_e32 v46, v164, v165
	v_exp_f32_e32 v60, v47
	v_add_f32_e32 v46, 0, v46
	v_add_f32_e32 v47, v210, v211
	v_add_f32_e32 v62, v47, v46
	v_cvt_pk_bf16_f32 v32, v39, v38
	v_cvt_pk_bf16_f32 v33, v41, v40
	v_cvt_pk_bf16_f32 v34, v43, v42
	v_cvt_pk_bf16_f32 v35, v45, v44
	v_add_f32_e32 v63, v212, v213
	v_add_f32_e32 v46, v63, v62
	v_mfma_f32_32x32x16_bf16 v[0:15], v[124:127], v[32:35], v[0:15]
	v_add_f32_e32 v47, v214, v215
	v_add_f32_e32 v62, v47, v46
	v_add_f32_e64 v46, v48, v50
	v_add_f32_e64 v47, v49, v51
	v_add_f32_e64 v36, v36, v52
	v_add_f32_e64 v37, v37, v53
	v_add_f32_e32 v47, v47, v62
	v_add_f32_e32 v46, v46, v47
	v_add_f32_e32 v37, v37, v46
	s_waitcnt vmcnt(2)
	v_mfma_f32_32x32x16_bf16 v[16:31], v[132:135], v[32:35], v[16:31]
	v_pk_mov_b32 v[46:47], v[52:53], v[52:53] op_sel:[1,0]
	v_cvt_pk_bf16_f32 v32, v165, v211
	v_cvt_pk_bf16_f32 v33, v213, v215
	v_cvt_pk_bf16_f32 v34, v51, v50
	v_cvt_pk_bf16_f32 v35, v46, v47
	v_add_f32_e32 v46, v36, v37
	v_pk_add_f32 v[36:37], v[38:39], v[54:55]
	v_mfma_f32_32x32x16_bf16 v[0:15], v[120:123], v[32:35], v[0:15]
	v_add_f32_e32 v37, v37, v46
	v_add_f32_e32 v38, v36, v37
	v_add_f32_e64 v36, v40, v56
	v_add_f32_e64 v37, v41, v57
	s_add_i32 s16, s16, -1
	v_add_f32_e32 v37, v37, v38
	s_add_u32 s12, s12, 0x30000
	s_waitcnt vmcnt(1)
	v_mfma_f32_32x32x16_bf16 v[16:31], v[128:131], v[32:35], v[16:31]
	v_cvt_pk_bf16_f32 v32, v55, v54
	v_cvt_pk_bf16_f32 v33, v57, v56
	v_pk_mov_b32 v[38:39], v[60:61], v[60:61] op_sel:[1,0]
	v_cvt_pk_bf16_f32 v34, v59, v58
	v_cvt_pk_bf16_f32 v35, v38, v39
	v_add_f32_e32 v38, v36, v37
	v_pk_add_f32 v[36:37], v[42:43], v[58:59]
	v_mfma_f32_32x32x16_bf16 v[0:15], v[112:115], v[32:35], v[0:15]
	v_add_f32_e32 v37, v37, v38
	v_add_f32_e32 v38, v36, v37
	v_add_f32_e64 v36, v44, v60
	v_add_f32_e64 v37, v45, v61
	s_addc_u32 s13, s13, 0
	v_add_f32_e32 v37, v37, v38
	v_add_f32_e32 v36, v36, v37
	v_add_f32_e32 v209, v209, v36
	s_waitcnt vmcnt(0)
	v_mfma_f32_32x32x16_bf16 v[16:31], v[116:119], v[32:35], v[16:31]
	s_cmp_lg_u32 s40, s12
	v_add_u32_e32 v208, 0xffffff00, v208
	s_cbranch_scc0 .LBB0_1023
.LBB0_1032:
	s_add_u32 s100, s98, s12
	s_addc_u32 s101, s99, s13
	s_add_u32 s100, s100, 0xdb00000
	s_addc_u32 s101, s101, 0
	global_load_dwordx4 v[136:139], v226, s[100:101] offset:2048
	global_load_dwordx4 v[124:127], v227, s[100:101] offset:2048
	global_load_dwordx4 v[120:123], v228, s[100:101] offset:2048
	global_load_dwordx4 v[112:115], v229, s[100:101] offset:2048
	global_load_dwordx4 v[140:143], v230, s[100:101] offset:2048
	global_load_dwordx4 v[132:135], v231, s[100:101] offset:2048
	global_load_dwordx4 v[128:131], v232, s[100:101] offset:2048
	global_load_dwordx4 v[116:119], v233, s[100:101] offset:2048
	s_cmp_lt_u32 s16, 5
	s_cbranch_scc0 .LBB0_1038
	s_cmp_lg_u32 s39, s12
	s_mov_b64 s[14:15], -1
	s_cbranch_scc0 .LBB0_1035
	ds_read2_b32 v[48:49], v208 offset0:59 offset1:58
	ds_read2_b32 v[50:51], v208 offset0:57 offset1:56
	ds_read2_b32 v[52:53], v208 offset0:51 offset1:50
	ds_read2_b32 v[54:55], v208 offset0:49 offset1:48
	ds_read2_b32 v[32:33], v208 offset0:27 offset1:26
	ds_read2_b32 v[34:35], v208 offset0:25 offset1:24
	ds_read2_b32 v[36:37], v208 offset0:19 offset1:18
	ds_read2_b32 v[38:39], v208 offset0:17 offset1:16
	ds_read2_b32 v[56:57], v208 offset0:43 offset1:42
	ds_read2_b32 v[58:59], v208 offset0:41 offset1:40
	ds_read2_b32 v[60:61], v208 offset0:35 offset1:34
	ds_read2_b32 v[62:63], v208 offset0:33 offset1:32
	ds_read2_b32 v[40:41], v208 offset0:11 offset1:10
	ds_read2_b32 v[42:43], v208 offset0:9 offset1:8
	ds_read2_b32 v[44:45], v208 offset0:3 offset1:2
	ds_read2_b32 v[46:47], v208 offset0:1 offset1:0
	s_mov_b64 s[14:15], 0

; __device__ __forceinline__ void attn_unit(const Params& p, const LAS float* bl, LAS bf16_t* stg, int unit, int lane) {
;     ...
; #pragma unroll
;         for (int d0 = 0; d0 < 4; ++d0) {
;             s0 = __builtin_amdgcn_mfma_f32_32x32x16_bf16(__builtin_bit_cast(bf16x8, kc[d0]), qf[d0], s0, 0, 0, 0);
;             s1 = __builtin_amdgcn_mfma_f32_32x32x16_bf16(__builtin_bit_cast(bf16x8, kc[4 + d0]), qf[d0], s1, 0, 0, 0);
;         }
;         if (dlt > 0) { const bf16_t* kblk = PB + (krow0 + 64) * NPB + 512 + h * 64;
; #pragma unroll
;           for (int f = 0; f < 8; ++f) kc[f] = *FRAGP(kblk, f); }
.LBB0_1040:
	s_waitcnt vmcnt(15) lgkmcnt(1)
	s_nop 0
	v_mfma_f32_32x32x16_bf16 v[48:63], v[80:83], v[64:67], v[48:63]
	s_cmp_eq_u32 s17, s12
	s_waitcnt vmcnt(11) lgkmcnt(0)
	v_mfma_f32_32x32x16_bf16 v[32:47], v[96:99], v[64:67], v[32:47]
	v_mfma_f32_32x32x16_bf16 v[48:63], v[84:87], v[68:71], v[48:63]
	s_waitcnt vmcnt(10)
	v_mfma_f32_32x32x16_bf16 v[32:47], v[100:103], v[68:71], v[32:47]
	v_mfma_f32_32x32x16_bf16 v[48:63], v[88:91], v[72:75], v[48:63]
	s_waitcnt vmcnt(9)
	v_mfma_f32_32x32x16_bf16 v[32:47], v[104:107], v[72:75], v[32:47]
	v_mfma_f32_32x32x16_bf16 v[48:63], v[92:95], v[76:79], v[48:63]
	s_waitcnt vmcnt(8)
	v_mfma_f32_32x32x16_bf16 v[32:47], v[108:111], v[76:79], v[32:47]
	s_cbranch_scc1 .LBB0_1031
	s_add_u32 s100, s100, 0x30000
	s_addc_u32 s101, s101, 0
	global_load_dwordx4 v[80:83], v226, s[100:101] offset:1024
	global_load_dwordx4 v[84:87], v227, s[100:101] offset:1024
	global_load_dwordx4 v[88:91], v228, s[100:101] offset:1024
	global_load_dwordx4 v[92:95], v229, s[100:101] offset:1024
	global_load_dwordx4 v[96:99], v230, s[100:101] offset:1024
	global_load_dwordx4 v[100:103], v231, s[100:101] offset:1024
	global_load_dwordx4 v[104:107], v232, s[100:101] offset:1024
	global_load_dwordx4 v[108:111], v233, s[100:101] offset:1024
	s_branch .LBB0_1031
